# hyena: channel->workgroup remap so each XCD owns 32 adjacent channels (its 2-byte column stores fill whole 64-byte sectors in one L2) (on top of v5)
# speedup vs baseline: 1.0137x; 1.0137x over previous
.LBB0_466:
	s_or_b64 exec, exec, s[2:3]
	v_readlane_b32 s0, v255, 18
	v_readlane_b32 s1, v255, 19
	s_and_b64 vcc, exec, s[0:1]
	s_mov_b32 s2, s80
	s_cmp_eq_u32 s94, 0x100
	s_cbranch_scc0 .Lhy_noremap
	s_and_b32 s2, s80, 7
	s_lshl_b32 s2, s2, 5
	s_lshr_b32 s3, s80, 3
	s_or_b32 s2, s2, s3
.Lhy_noremap:
	s_waitcnt lgkmcnt(0)
	s_barrier
	s_cbranch_vccz .LBB0_473
